# second streaming-phase block start: the two independent pointer-table loads issued together with one wait (on top of v36 norm hoist + v35 staging fixes)
# speedup vs baseline: 1.0031x; 1.0029x over previous
; #define LAS __attribute__((address_space(3)))
; #define TID_OF(a) ((a).w0 * 64 + lane_opaque())
; #define INP(a, i) inp_(a, i)
; DI void gngate_phase(unsigned char* lds, const Ctx& a, const Op& d) {
;     ...
;         const int t_ = TID_OF(a);
;         const float *s0 = INP(a, 19) + ia * DM, *s1 = INP(a, 20) + ia * DM, *s2 = INP(a, 21) + ia * DM, *s3 = INP(a, 22) + ia * DM;
;         for (int i = t_ * 4; i < DM; i += NTHREADS * 4) { *(LAS f32x4*)(pl + i) = *(const f32x4*)(s0 + i); *(LAS f32x4*)(pl + DM + i) = *(const f32x4*)(s1 + i);
.LBB0_426:
	v_mov_b64_e32 v[6:7], s[58:59]
	v_mbcnt_lo_u32_b32 v1, -1, 0
	v_mbcnt_hi_u32_b32 v1, -1, v1
	flat_load_dwordx4 v[2:5], v[6:7] offset:152
	flat_load_dwordx4 v[10:13], v[6:7] offset:168
	v_readlane_b32 s8, v231, 22
	s_waitcnt vmcnt(0) lgkmcnt(0)
	v_readfirstlane_b32 s0, v2
	v_readfirstlane_b32 s1, v3
	v_readfirstlane_b32 s4, v4
	v_readfirstlane_b32 s5, v5
	v_readfirstlane_b32 s6, v10
	v_lshlrev_b32_e32 v2, 2, v1
	v_add_u32_e32 v0, s8, v2
	s_movk_i32 s8, 0x800
	v_readfirstlane_b32 s7, v11
	v_readfirstlane_b32 s10, v12
	v_readfirstlane_b32 s11, v13
	v_cmp_gt_i32_e32 vcc, s8, v0
	s_and_saveexec_b64 s[8:9], vcc
	s_mov_b64 s[14:15], 0x2000
	s_cbranch_execz .LBB0_429
	v_readlane_b32 s12, v231, 22
	s_addk_i32 s12, 0xf800
	s_nop 0
	v_add_u32_e32 v8, s12, v2
	s_add_i32 s12, s62, 0
	v_lshl_add_u32 v9, v1, 4, s12
	v_ashrrev_i32_e32 v1, 31, v0
	v_readlane_b32 s12, v231, 20
	v_lshlrev_b64 v[0:1], 2, v[0:1]
	v_readlane_b32 s13, v231, 21
	s_nop 1
	v_lshl_add_u64 v[6:7], s[12:13], 2, v[0:1]
	v_lshl_add_u64 v[0:1], s[10:11], 0, v[6:7]
	v_lshl_add_u64 v[2:3], s[6:7], 0, v[6:7]
	v_lshl_add_u64 v[4:5], s[4:5], 0, v[6:7]
	v_lshl_add_u64 v[6:7], s[0:1], 0, v[6:7]
	s_mov_b64 s[0:1], 0
